# placement check after the first grid barrier: the four XCC-table loads issued together (one round trip instead of two)
# speedup vs baseline: 1.0013x; 1.0013x over previous
; __global__ void __launch_bounds__(NWAVES * 64, 2) mk_fwd(Args args) {
;     ...
;     if (N_LAUNCHES == 1 && IN(0) && IN(1) && G == 256) {
;         if (wave == 0) {
;             const int t = tid;
;             const unsigned* tab = ctl + CW_XCCTAB + (t >> 3) + 8 * (t & 7);
;             const unsigned i0 = tab[0], i1 = tab[64], i2 = tab[128], i3 = tab[192];
;             const bool same = (i0 != 0u) && (i0 == i1) && (i0 == i2) && (i0 == i3);
;             const bool all = __all(same);
;             if (tid == 0) MISC[12] = all ? 1u : 0u;
;         }
;         __syncthreads();
;         xl_fast = (MISC[12] != 0u);
;     }
.LBB0_104:
	s_cmpk_eq_i32 s96, 0x100
	s_cselect_b64 s[2:3], -1, 0
	s_cmpk_lg_i32 s96, 0x100
	s_cselect_b64 s[6:7], -1, 0
	v_writelane_b32 v242, s6, 45
	s_mov_b64 s[36:37], 0
	s_nop 0
	v_writelane_b32 v242, s7, 46
	v_writelane_b32 v242, s2, 47
	s_and_b64 s[4:5], s[4:5], s[2:3]
	s_andn2_b64 vcc, exec, s[4:5]
	v_writelane_b32 v242, s3, 48
	s_cbranch_vccnz .LBB0_112
	s_cmp_gt_u32 s33, 63
	s_cbranch_scc1 .LBB0_111
	v_lshrrev_b32_e32 v1, 1, v0
	v_readlane_b32 s4, v242, 22
	v_and_b32_e32 v2, 0xfc, v1
	v_mov_b32_e32 v3, 0
	v_readlane_b32 s18, v242, 36
	v_readlane_b32 s19, v242, 37
	v_lshlrev_b32_e32 v1, 5, v0
	v_readlane_b32 s5, v242, 23
	v_lshl_add_u64 v[4:5], s[18:19], 0, v[2:3]
	v_and_b32_e32 v2, 0xe0, v1
	v_lshl_add_u64 v[2:3], v[4:5], 0, v[2:3]
	v_add_co_u32_e32 v4, vcc, 0x10000, v2
	v_readlane_b32 s6, v242, 24
	s_nop 0
	v_addc_co_u32_e32 v5, vcc, 0, v3, vcc
	global_load_dword v1, v[4:5], off
	global_load_dword v6, v[4:5], off offset:256
	global_load_dword v7, v[4:5], off offset:512
	global_load_dword v8, v[4:5], off offset:768
	v_readlane_b32 s7, v242, 25
	s_mov_b64 s[4:5], 0
	v_readlane_b32 s8, v242, 26
	v_readlane_b32 s9, v242, 27
	v_readlane_b32 s10, v242, 28
	v_readlane_b32 s11, v242, 29
	v_readlane_b32 s12, v242, 30
	v_readlane_b32 s13, v242, 31
	v_readlane_b32 s14, v242, 32
	v_readlane_b32 s15, v242, 33
	v_readlane_b32 s16, v242, 34
	v_readlane_b32 s17, v242, 35
	s_waitcnt vmcnt(0)
	v_cmp_eq_u32_e64 s[4:5], v1, v6
	v_cmp_ne_u32_e32 vcc, 0, v1
	s_and_b64 s[4:5], vcc, s[4:5]
	v_cmp_eq_u32_e32 vcc, v1, v7
	s_and_b64 s[4:5], s[4:5], vcc
	v_cmp_eq_u32_e32 vcc, v1, v8
	s_and_b64 s[4:5], s[4:5], vcc
	s_and_b64 s[4:5], s[4:5], exec
.LBB0_108:
	v_cndmask_b32_e64 v1, 0, 1, s[4:5]
	v_readlane_b32 s2, v242, 38
	s_mov_b64 s[6:7], exec
	v_cmp_ne_u32_e32 vcc, 0, v1
	v_readlane_b32 s3, v242, 39
	s_and_saveexec_b64 s[4:5], s[2:3]
	s_cbranch_execz .LBB0_110
	s_cmp_eq_u64 vcc, s[6:7]
	s_cselect_b64 s[6:7], -1, 0
	v_cndmask_b32_e64 v1, 0, 1, s[6:7]
	s_add_i32 s6, 0, 0x21170
	v_mov_b32_e32 v2, s6
	ds_write_b32 v2, v1
